# P1 tile order v4: block permutation optimised with per-kind tile costs measured on chip (plain 25.3us, transposed +2.2, decay column +7, sample rows +3.7); mem-tile WGs stop after round 4
# baseline (speedup 1.0000x reference)
.Lp1r1:
	s_mov_b32 s98, 0xf73501
	s_cmp_eq_u32 s99, 1
	s_cmov_b32 s98, 0xba14f8
	s_cmp_eq_u32 s99, 2
	s_cmov_b32 s98, 0xb3207b
	s_cmp_eq_u32 s99, 3
	s_cmov_b32 s98, 0xba3057
	s_cmp_eq_u32 s99, 4
	s_cmov_b32 s98, 0xc2f711
	s_cmp_eq_u32 s99, 5
	s_cmov_b32 s98, 0xb320f9
	s_cmp_eq_u32 s99, 6
	s_cmov_b32 s98, 0x5710fc
	s_cmp_eq_u32 s99, 7
	s_cmov_b32 s98, 0x60afac
	s_branch .Lp1rdone
.Lp1r2:
	s_mov_b32 s98, 0xd0b1ea
	s_cmp_eq_u32 s99, 1
	s_cmov_b32 s98, 0x366ec2
	s_cmp_eq_u32 s99, 2
	s_cmov_b32 s98, 0x3aa0fc
	s_cmp_eq_u32 s99, 3
	s_cmov_b32 s98, 0xfac2d0
	s_cmp_eq_u32 s99, 4
	s_cmov_b32 s98, 0xcac23b
	s_cmp_eq_u32 s99, 5
	s_cmov_b32 s98, 0x7543b8
	s_cmp_eq_u32 s99, 6
	s_cmov_b32 s98, 0xac45f1
	s_cmp_eq_u32 s99, 7
	s_cmov_b32 s98, 0x99a14f
	s_branch .Lp1rdone
.Lp1r3:
	s_mov_b32 s98, 0xf4851e
	s_cmp_eq_u32 s99, 1
	s_cmov_b32 s98, 0x6bd846
	s_cmp_eq_u32 s99, 2
	s_cmov_b32 s98, 0xab72c4
	s_cmp_eq_u32 s99, 3
	s_cmov_b32 s98, 0xdd4ac8
	s_cmp_eq_u32 s99, 4
	s_cmov_b32 s98, 0x477744
	s_cmp_eq_u32 s99, 5
	s_cmov_b32 s98, 0xb9f302
	s_cmp_eq_u32 s99, 6
	s_cmov_b32 s98, 0xf95318
	s_cmp_eq_u32 s99, 7
	s_cmov_b32 s98, 0xab423b
	s_branch .Lp1rdone
.Lp1r4:
	s_mov_b32 s98, 0xa54e1e
	s_cmp_eq_u32 s99, 1
	s_cmov_b32 s98, 0x32a63e
	s_cmp_eq_u32 s99, 2
	s_cmov_b32 s98, 0x745dd
	s_cmp_eq_u32 s99, 3
	s_cmov_b32 s98, 0x3bd423
	s_cmp_eq_u32 s99, 4
	s_cmov_b32 s98, 0x37851e
	s_cmp_eq_u32 s99, 5
	s_cmov_b32 s98, 0xd170cd
	s_cmp_eq_u32 s99, 6
	s_cmov_b32 s98, 0x315787
	s_cmp_eq_u32 s99, 7
	s_cmov_b32 s98, 0x87d782
	s_branch .Lp1rdone
.Lp1r5:
	s_mov_b32 s98, 0x19d9d1
	s_cmp_eq_u32 s99, 1
	s_cmov_b32 s98, 0xcbb161
	s_cmp_eq_u32 s99, 2
	s_cmov_b32 s98, 0xe9e845
	s_cmp_eq_u32 s99, 3
	s_cmov_b32 s98, 0x23eaa3
	s_cmp_eq_u32 s99, 4
	s_cmov_b32 s98, 0x53e358
	s_cmp_eq_u32 s99, 5
	s_cmov_b32 s98, 0x9970e9
	s_cmp_eq_u32 s99, 6
	s_cmov_b32 s98, 0xf66283
	s_cmp_eq_u32 s99, 7
	s_cmov_b32 s98, 0xdec688
	s_branch .Lp1rdone
.Lp1r6:
	s_mov_b32 s98, 0xabe2e0
	s_cmp_eq_u32 s99, 1
	s_cmov_b32 s98, 0xb10c7b
	s_cmp_eq_u32 s99, 2
	s_cmov_b32 s98, 0xb98539
	s_cmp_eq_u32 s99, 3
	s_cmov_b32 s98, 0xfa9702
	s_cmp_eq_u32 s99, 4
	s_cmov_b32 s98, 0xc7d4c4
	s_cmp_eq_u32 s99, 5
	s_cmov_b32 s98, 0xbe6099
	s_cmp_eq_u32 s99, 6
	s_cmov_b32 s98, 0xbce81a
	s_cmp_eq_u32 s99, 7
	s_cmov_b32 s98, 0xf354c8

.Lp1sp_nomem:
	s_cmp_lg_u32 s71, 6
	s_cbranch_scc1 .Lp1sp_done
	s_sub_u32 s100, s98, 0x9a
	s_cmp_gt_u32 s100, 15
	s_cbranch_scc1 .Lp1sp_done
	s_lshr_b32 s100, s100, 3
	s_mov_b32 s101, 0x19d9d1
	s_cmp_eq_u32 s99, 1
	s_cmov_b32 s101, 0xcbb161
	s_cmp_eq_u32 s99, 2
	s_cmov_b32 s101, 0xe9e845
	s_cmp_eq_u32 s99, 3
	s_cmov_b32 s101, 0x23eaa3
	s_cmp_eq_u32 s99, 4
	s_cmov_b32 s101, 0x53e358
	s_cmp_eq_u32 s99, 5
	s_cmov_b32 s101, 0x9970e9
	s_cmp_eq_u32 s99, 6
	s_cmov_b32 s101, 0xf66283
	s_cmp_eq_u32 s99, 7
	s_cmov_b32 s101, 0xdec688
	s_lshr_b32 s101, s101, 21
	s_lshl_b32 s101, s101, 2
	s_or_b32 s101, s101, 2
	s_or_b32 s101, s101, s100
	s_lshl_b32 s101, s101, 3
	s_or_b32 s101, s101, s99
	s_add_u32 s10, s101, 0x500
	s_mov_b32 s11, 0
